# P9 epilogue row-scale loads and P7 mid-K ssqy loads pre-issued before each unit's K-loop (no loads or vmcnt waits in the epilogue / mid hook)
# speedup vs baseline: 1.0080x; 1.0080x over previous
.LBB0_541:
	s_ashr_i32 s25, s24, 31
	s_lshl_b64 s[8:9], s[24:25], 20
	s_add_u32 s26, s84, s8
	s_addc_u32 s27, s85, s9
	s_and_b64 s[8:9], s[6:7], exec
	s_cselect_b32 s3, s27, s37
	s_cselect_b32 s25, s26, s36
	s_ashr_i32 s23, s22, 31
	s_lshl_b64 s[8:9], s[22:23], 20
	s_add_u32 s28, s86, s8
	s_addc_u32 s29, s87, s9
	s_and_b64 s[8:9], s[6:7], exec
	s_cselect_b32 s23, s29, s1
	s_cselect_b32 s43, s28, s0
	s_lshl_b32 s8, s30, 9
	v_or_b32_e32 v1, 32, v186
	v_add_u32_e32 v4, s8, v1
	v_or_b32_e32 v1, 64, v186
	v_add_u32_e32 v6, s8, v1
	v_or_b32_e32 v1, 0x60, v186
	s_waitcnt lgkmcnt(0)
	v_add_u32_e32 v2, s8, v186
	v_add_u32_e32 v8, s8, v1
	v_add_u32_e32 v1, 0x100, v186
	v_ashrrev_i32_e32 v3, 31, v2
	v_add_u32_e32 v10, s8, v1
	v_add_u32_e32 v12, s8, v187
	v_add_u32_e32 v14, s8, v188
	v_add_u32_e32 v16, s8, v189
	v_ashrrev_i32_e32 v5, 31, v4
	v_ashrrev_i32_e32 v7, 31, v6
	v_ashrrev_i32_e32 v9, 31, v8
	v_ashrrev_i32_e32 v11, 31, v10
	v_ashrrev_i32_e32 v13, 31, v12
	v_ashrrev_i32_e32 v15, 31, v14
	v_ashrrev_i32_e32 v17, 31, v16
	v_lshl_add_u64 v[132:133], v[2:3], 2, s[54:55]
	v_mov_b32_e32 v2, v0
	v_mov_b32_e32 v3, v0
	v_lshl_add_u64 v[134:135], v[4:5], 2, s[54:55]
	v_lshl_add_u64 v[136:137], v[6:7], 2, s[54:55]
	v_lshl_add_u64 v[138:139], v[8:9], 2, s[54:55]
	v_lshl_add_u64 v[140:141], v[10:11], 2, s[54:55]
	v_lshl_add_u64 v[142:143], v[12:13], 2, s[54:55]
	v_lshl_add_u64 v[144:145], v[14:15], 2, s[54:55]
	v_lshl_add_u64 v[146:147], v[16:17], 2, s[54:55]
	global_load_dwordx2 v[132:133], v[132:133], off
	global_load_dwordx2 v[134:135], v[134:135], off
	global_load_dwordx2 v[136:137], v[136:137], off
	global_load_dwordx2 v[138:139], v[138:139], off
	global_load_dwordx2 v[140:141], v[140:141], off
	global_load_dwordx2 v[142:143], v[142:143], off
	global_load_dwordx2 v[144:145], v[144:145], off
	global_load_dwordx2 v[146:147], v[146:147], off
	s_add_u32 s61, s0, 0x100
	v_mov_b32_e32 v1, v0
	v_mov_b64_e32 v[6:7], v[2:3]
	v_mov_b64_e32 v[10:11], v[2:3]
	v_mov_b64_e32 v[22:23], v[2:3]
	v_mov_b64_e32 v[26:27], v[2:3]
	v_mov_b64_e32 v[38:39], v[2:3]
	v_mov_b64_e32 v[42:43], v[2:3]
	v_mov_b64_e32 v[54:55], v[2:3]
	v_mov_b64_e32 v[58:59], v[2:3]
	v_mov_b64_e32 v[14:15], v[2:3]
	v_mov_b64_e32 v[18:19], v[2:3]
	v_mov_b64_e32 v[30:31], v[2:3]
	v_mov_b64_e32 v[34:35], v[2:3]
	v_mov_b64_e32 v[46:47], v[2:3]
	v_mov_b64_e32 v[50:51], v[2:3]
	v_mov_b64_e32 v[62:63], v[2:3]
	v_mov_b64_e32 v[66:67], v[2:3]
	v_mov_b64_e32 v[70:71], v[2:3]
	v_mov_b64_e32 v[74:75], v[2:3]
	v_mov_b64_e32 v[86:87], v[2:3]
	v_mov_b64_e32 v[90:91], v[2:3]
	v_mov_b64_e32 v[102:103], v[2:3]
	v_mov_b64_e32 v[106:107], v[2:3]
	v_mov_b64_e32 v[118:119], v[2:3]
	v_mov_b64_e32 v[122:123], v[2:3]
	v_mov_b64_e32 v[78:79], v[2:3]
	v_mov_b64_e32 v[82:83], v[2:3]
	v_mov_b64_e32 v[94:95], v[2:3]
	v_mov_b64_e32 v[98:99], v[2:3]
	v_mov_b64_e32 v[110:111], v[2:3]
	v_mov_b64_e32 v[114:115], v[2:3]
	v_mov_b64_e32 v[126:127], v[2:3]
	v_mov_b64_e32 v[130:131], v[2:3]
	s_addc_u32 s62, s1, 0
	v_lshl_add_u64 v[148:149], s[36:37], 0, v[166:167]
	v_lshl_add_u64 v[150:151], s[36:37], 0, v[168:169]
	s_mov_b32 s63, -2
	s_mov_b64 s[38:39], 0
	v_mov_b64_e32 v[4:5], v[0:1]
	v_mov_b64_e32 v[8:9], v[0:1]
	v_mov_b64_e32 v[20:21], v[0:1]
	v_mov_b64_e32 v[24:25], v[0:1]
	v_mov_b64_e32 v[36:37], v[0:1]
	v_mov_b64_e32 v[40:41], v[0:1]
	v_mov_b64_e32 v[52:53], v[0:1]
	v_mov_b64_e32 v[56:57], v[0:1]
	v_mov_b64_e32 v[12:13], v[0:1]
	v_mov_b64_e32 v[16:17], v[0:1]
	v_mov_b64_e32 v[28:29], v[0:1]
	v_mov_b64_e32 v[32:33], v[0:1]
	v_mov_b64_e32 v[44:45], v[0:1]
	v_mov_b64_e32 v[48:49], v[0:1]
	v_mov_b64_e32 v[60:61], v[0:1]
	v_mov_b64_e32 v[64:65], v[0:1]
	v_mov_b64_e32 v[68:69], v[0:1]
	v_mov_b64_e32 v[72:73], v[0:1]
	v_mov_b64_e32 v[84:85], v[0:1]
	v_mov_b64_e32 v[88:89], v[0:1]
	v_mov_b64_e32 v[100:101], v[0:1]
	v_mov_b64_e32 v[104:105], v[0:1]
	v_mov_b64_e32 v[116:117], v[0:1]
	v_mov_b64_e32 v[120:121], v[0:1]
	v_mov_b64_e32 v[76:77], v[0:1]
	v_mov_b64_e32 v[80:81], v[0:1]
	v_mov_b64_e32 v[92:93], v[0:1]
	v_mov_b64_e32 v[96:97], v[0:1]
	v_mov_b64_e32 v[108:109], v[0:1]
	v_mov_b64_e32 v[112:113], v[0:1]
	v_mov_b64_e32 v[124:125], v[0:1]
	v_mov_b64_e32 v[128:129], v[0:1]
	s_branch .LBB0_543

.LBB0_543:
	s_cmpk_lg_i32 s38, 0x800
	s_cbranch_scc1 .LBB0_542
	v_fmamk_f32 v1, v132, 0x3a800000, v191
	v_cmp_gt_f32_e32 vcc, s56, v1
	v_mul_f32_e32 v2, 0x4b800000, v1
	s_nop 0
	v_cndmask_b32_e32 v1, v1, v2, vcc
	v_rsq_f32_e32 v1, v1
	s_nop 0
	v_mul_f32_e32 v2, 0x45800000, v1
	v_cndmask_b32_e32 v1, v1, v2, vcc
	v_fmamk_f32 v2, v133, 0x3a800000, v191
	v_cmp_gt_f32_e32 vcc, s57, v2
	v_mul_f32_e32 v3, 0x4f800000, v2
	s_nop 0
	v_cndmask_b32_e32 v2, v2, v3, vcc
	v_sqrt_f32_e32 v3, v2
	s_nop 0
	v_add_u32_e32 v152, -1, v3
	v_fma_f32 v153, -v152, v3, v2
	v_cmp_ge_f32_e64 s[8:9], 0, v153
	v_add_u32_e32 v153, 1, v3
	s_nop 0
	v_cndmask_b32_e64 v152, v3, v152, s[8:9]
	v_fma_f32 v3, -v153, v3, v2
	v_cmp_lt_f32_e64 s[8:9], 0, v3
	s_nop 1
	v_cndmask_b32_e64 v3, v152, v153, s[8:9]
	v_mul_f32_e32 v152, 0x37800000, v3
	v_cndmask_b32_e32 v3, v3, v152, vcc
	v_cmp_class_f32_e32 vcc, v2, v192
	s_nop 1
	v_cndmask_b32_e32 v2, v3, v2, vcc
	v_mul_f32_e32 v2, v2, v1
	v_pk_mul_f32 v[130:131], v[130:131], v[2:3] op_sel_hi:[1,0]
	v_pk_mul_f32 v[128:129], v[128:129], v[2:3] op_sel_hi:[1,0]
	v_pk_mul_f32 v[126:127], v[126:127], v[2:3] op_sel_hi:[1,0]
	v_pk_mul_f32 v[124:125], v[124:125], v[2:3] op_sel_hi:[1,0]
	v_pk_mul_f32 v[122:123], v[122:123], v[2:3] op_sel_hi:[1,0]
	v_pk_mul_f32 v[120:121], v[120:121], v[2:3] op_sel_hi:[1,0]
	v_pk_mul_f32 v[118:119], v[118:119], v[2:3] op_sel_hi:[1,0]
	v_pk_mul_f32 v[116:117], v[116:117], v[2:3] op_sel_hi:[1,0]
	v_fmamk_f32 v1, v134, 0x3a800000, v191
	v_cmp_gt_f32_e32 vcc, s56, v1
	v_mul_f32_e32 v2, 0x4b800000, v1
	s_nop 0
	v_cndmask_b32_e32 v1, v1, v2, vcc
	v_rsq_f32_e32 v1, v1
	s_nop 0
	v_mul_f32_e32 v2, 0x45800000, v1
	v_cndmask_b32_e32 v1, v1, v2, vcc
	v_fmamk_f32 v2, v135, 0x3a800000, v191
	v_cmp_gt_f32_e32 vcc, s57, v2
	v_mul_f32_e32 v3, 0x4f800000, v2
	s_nop 0
	v_cndmask_b32_e32 v2, v2, v3, vcc
	v_sqrt_f32_e32 v3, v2
	s_nop 0
	v_add_u32_e32 v152, -1, v3
	v_fma_f32 v153, -v152, v3, v2
	v_cmp_ge_f32_e64 s[8:9], 0, v153
	v_add_u32_e32 v153, 1, v3
	s_nop 0
	v_cndmask_b32_e64 v152, v3, v152, s[8:9]
	v_fma_f32 v3, -v153, v3, v2
	v_cmp_lt_f32_e64 s[8:9], 0, v3
	s_nop 1
	v_cndmask_b32_e64 v3, v152, v153, s[8:9]
	v_mul_f32_e32 v152, 0x37800000, v3
	v_cndmask_b32_e32 v3, v3, v152, vcc
	v_cmp_class_f32_e32 vcc, v2, v192
	s_nop 1
	v_cndmask_b32_e32 v2, v3, v2, vcc
	v_mul_f32_e32 v2, v2, v1
	v_pk_mul_f32 v[114:115], v[114:115], v[2:3] op_sel_hi:[1,0]
	v_pk_mul_f32 v[112:113], v[112:113], v[2:3] op_sel_hi:[1,0]
	v_pk_mul_f32 v[110:111], v[110:111], v[2:3] op_sel_hi:[1,0]
	v_pk_mul_f32 v[108:109], v[108:109], v[2:3] op_sel_hi:[1,0]
	v_pk_mul_f32 v[106:107], v[106:107], v[2:3] op_sel_hi:[1,0]
	v_pk_mul_f32 v[104:105], v[104:105], v[2:3] op_sel_hi:[1,0]
	v_pk_mul_f32 v[102:103], v[102:103], v[2:3] op_sel_hi:[1,0]
	v_pk_mul_f32 v[100:101], v[100:101], v[2:3] op_sel_hi:[1,0]
	v_fmamk_f32 v1, v136, 0x3a800000, v191
	v_cmp_gt_f32_e32 vcc, s56, v1
	v_mul_f32_e32 v2, 0x4b800000, v1
	s_nop 0
	v_cndmask_b32_e32 v1, v1, v2, vcc
	v_rsq_f32_e32 v1, v1
	s_nop 0
	v_mul_f32_e32 v2, 0x45800000, v1
	v_cndmask_b32_e32 v1, v1, v2, vcc
	v_fmamk_f32 v2, v137, 0x3a800000, v191
	v_cmp_gt_f32_e32 vcc, s57, v2
	v_mul_f32_e32 v3, 0x4f800000, v2
	s_nop 0
	v_cndmask_b32_e32 v2, v2, v3, vcc
	v_sqrt_f32_e32 v3, v2
	s_nop 0
	v_add_u32_e32 v152, -1, v3
	v_fma_f32 v153, -v152, v3, v2
	v_cmp_ge_f32_e64 s[8:9], 0, v153
	v_add_u32_e32 v153, 1, v3
	s_nop 0
	v_cndmask_b32_e64 v152, v3, v152, s[8:9]
	v_fma_f32 v3, -v153, v3, v2
	v_cmp_lt_f32_e64 s[8:9], 0, v3
	s_nop 1
	v_cndmask_b32_e64 v3, v152, v153, s[8:9]
	v_mul_f32_e32 v152, 0x37800000, v3
	v_cndmask_b32_e32 v3, v3, v152, vcc
	v_cmp_class_f32_e32 vcc, v2, v192
	s_nop 1
	v_cndmask_b32_e32 v2, v3, v2, vcc
	v_mul_f32_e32 v2, v2, v1
	v_pk_mul_f32 v[98:99], v[98:99], v[2:3] op_sel_hi:[1,0]
	v_pk_mul_f32 v[96:97], v[96:97], v[2:3] op_sel_hi:[1,0]
	v_pk_mul_f32 v[94:95], v[94:95], v[2:3] op_sel_hi:[1,0]
	v_pk_mul_f32 v[92:93], v[92:93], v[2:3] op_sel_hi:[1,0]
	v_pk_mul_f32 v[90:91], v[90:91], v[2:3] op_sel_hi:[1,0]
	v_pk_mul_f32 v[88:89], v[88:89], v[2:3] op_sel_hi:[1,0]
	v_pk_mul_f32 v[86:87], v[86:87], v[2:3] op_sel_hi:[1,0]
	v_pk_mul_f32 v[84:85], v[84:85], v[2:3] op_sel_hi:[1,0]
	v_fmamk_f32 v1, v138, 0x3a800000, v191
	v_cmp_gt_f32_e32 vcc, s56, v1
	v_mul_f32_e32 v2, 0x4b800000, v1
	s_nop 0
	v_cndmask_b32_e32 v1, v1, v2, vcc
	v_rsq_f32_e32 v1, v1
	s_nop 0
	v_mul_f32_e32 v2, 0x45800000, v1
	v_cndmask_b32_e32 v1, v1, v2, vcc
	v_fmamk_f32 v2, v139, 0x3a800000, v191
	v_cmp_gt_f32_e32 vcc, s57, v2
	v_mul_f32_e32 v3, 0x4f800000, v2
	s_nop 0
	v_cndmask_b32_e32 v2, v2, v3, vcc
	v_sqrt_f32_e32 v3, v2
	s_nop 0
	v_add_u32_e32 v152, -1, v3
	v_fma_f32 v153, -v152, v3, v2
	v_cmp_ge_f32_e64 s[8:9], 0, v153
	v_add_u32_e32 v153, 1, v3
	s_nop 0
	v_cndmask_b32_e64 v152, v3, v152, s[8:9]
	v_fma_f32 v3, -v153, v3, v2
	v_cmp_lt_f32_e64 s[8:9], 0, v3
	s_nop 1
	v_cndmask_b32_e64 v3, v152, v153, s[8:9]
	v_mul_f32_e32 v152, 0x37800000, v3
	v_cndmask_b32_e32 v3, v3, v152, vcc
	v_cmp_class_f32_e32 vcc, v2, v192
	s_nop 1
	v_cndmask_b32_e32 v2, v3, v2, vcc
	v_mul_f32_e32 v2, v2, v1
	v_pk_mul_f32 v[82:83], v[82:83], v[2:3] op_sel_hi:[1,0]
	v_pk_mul_f32 v[80:81], v[80:81], v[2:3] op_sel_hi:[1,0]
	v_pk_mul_f32 v[78:79], v[78:79], v[2:3] op_sel_hi:[1,0]
	v_pk_mul_f32 v[76:77], v[76:77], v[2:3] op_sel_hi:[1,0]
	v_pk_mul_f32 v[74:75], v[74:75], v[2:3] op_sel_hi:[1,0]
	v_pk_mul_f32 v[72:73], v[72:73], v[2:3] op_sel_hi:[1,0]
	v_pk_mul_f32 v[70:71], v[70:71], v[2:3] op_sel_hi:[1,0]
	v_pk_mul_f32 v[68:69], v[68:69], v[2:3] op_sel_hi:[1,0]
	v_fmamk_f32 v1, v140, 0x3a800000, v191
	v_cmp_gt_f32_e32 vcc, s56, v1
	v_mul_f32_e32 v2, 0x4b800000, v1
	s_nop 0
	v_cndmask_b32_e32 v1, v1, v2, vcc
	v_rsq_f32_e32 v1, v1
	s_nop 0
	v_mul_f32_e32 v2, 0x45800000, v1
	v_cndmask_b32_e32 v1, v1, v2, vcc
	v_fmamk_f32 v2, v141, 0x3a800000, v191
	v_cmp_gt_f32_e32 vcc, s57, v2
	v_mul_f32_e32 v3, 0x4f800000, v2
	s_nop 0
	v_cndmask_b32_e32 v2, v2, v3, vcc
	v_sqrt_f32_e32 v3, v2
	s_nop 0
	v_add_u32_e32 v152, -1, v3
	v_fma_f32 v153, -v152, v3, v2
	v_cmp_ge_f32_e64 s[8:9], 0, v153
	v_add_u32_e32 v153, 1, v3
	s_nop 0
	v_cndmask_b32_e64 v152, v3, v152, s[8:9]
	v_fma_f32 v3, -v153, v3, v2
	v_cmp_lt_f32_e64 s[8:9], 0, v3
	s_nop 1
	v_cndmask_b32_e64 v3, v152, v153, s[8:9]
	v_mul_f32_e32 v152, 0x37800000, v3
	v_cndmask_b32_e32 v3, v3, v152, vcc
	v_cmp_class_f32_e32 vcc, v2, v192
	s_nop 1
	v_cndmask_b32_e32 v2, v3, v2, vcc
	v_mul_f32_e32 v2, v2, v1
	v_pk_mul_f32 v[66:67], v[66:67], v[2:3] op_sel_hi:[1,0]
	v_pk_mul_f32 v[64:65], v[64:65], v[2:3] op_sel_hi:[1,0]
	v_pk_mul_f32 v[62:63], v[62:63], v[2:3] op_sel_hi:[1,0]
	v_pk_mul_f32 v[60:61], v[60:61], v[2:3] op_sel_hi:[1,0]
	v_pk_mul_f32 v[58:59], v[58:59], v[2:3] op_sel_hi:[1,0]
	v_pk_mul_f32 v[56:57], v[56:57], v[2:3] op_sel_hi:[1,0]
	v_pk_mul_f32 v[54:55], v[54:55], v[2:3] op_sel_hi:[1,0]
	v_pk_mul_f32 v[52:53], v[52:53], v[2:3] op_sel_hi:[1,0]
	v_fmamk_f32 v1, v142, 0x3a800000, v191
	v_cmp_gt_f32_e32 vcc, s56, v1
	v_mul_f32_e32 v2, 0x4b800000, v1
	s_nop 0
	v_cndmask_b32_e32 v1, v1, v2, vcc
	v_rsq_f32_e32 v1, v1
	s_nop 0
	v_mul_f32_e32 v2, 0x45800000, v1
	v_cndmask_b32_e32 v1, v1, v2, vcc
	v_fmamk_f32 v2, v143, 0x3a800000, v191
	v_cmp_gt_f32_e32 vcc, s57, v2
	v_mul_f32_e32 v3, 0x4f800000, v2
	s_nop 0
	v_cndmask_b32_e32 v2, v2, v3, vcc
	v_sqrt_f32_e32 v3, v2
	s_nop 0
	v_add_u32_e32 v152, -1, v3
	v_fma_f32 v153, -v152, v3, v2
	v_cmp_ge_f32_e64 s[8:9], 0, v153
	v_add_u32_e32 v153, 1, v3
	s_nop 0
	v_cndmask_b32_e64 v152, v3, v152, s[8:9]
	v_fma_f32 v3, -v153, v3, v2
	v_cmp_lt_f32_e64 s[8:9], 0, v3
	s_nop 1
	v_cndmask_b32_e64 v3, v152, v153, s[8:9]
	v_mul_f32_e32 v152, 0x37800000, v3
	v_cndmask_b32_e32 v3, v3, v152, vcc
	v_cmp_class_f32_e32 vcc, v2, v192
	s_nop 1
	v_cndmask_b32_e32 v2, v3, v2, vcc
	v_mul_f32_e32 v2, v2, v1
	v_pk_mul_f32 v[50:51], v[50:51], v[2:3] op_sel_hi:[1,0]
	v_pk_mul_f32 v[48:49], v[48:49], v[2:3] op_sel_hi:[1,0]
	v_pk_mul_f32 v[46:47], v[46:47], v[2:3] op_sel_hi:[1,0]
	v_pk_mul_f32 v[44:45], v[44:45], v[2:3] op_sel_hi:[1,0]
	v_pk_mul_f32 v[42:43], v[42:43], v[2:3] op_sel_hi:[1,0]
	v_pk_mul_f32 v[40:41], v[40:41], v[2:3] op_sel_hi:[1,0]
	v_pk_mul_f32 v[38:39], v[38:39], v[2:3] op_sel_hi:[1,0]
	v_pk_mul_f32 v[36:37], v[36:37], v[2:3] op_sel_hi:[1,0]
	v_fmamk_f32 v1, v144, 0x3a800000, v191
	v_cmp_gt_f32_e32 vcc, s56, v1
	v_mul_f32_e32 v2, 0x4b800000, v1
	s_nop 0
	v_cndmask_b32_e32 v1, v1, v2, vcc
	v_rsq_f32_e32 v1, v1
	s_nop 0
	v_mul_f32_e32 v2, 0x45800000, v1
	v_cndmask_b32_e32 v1, v1, v2, vcc
	v_fmamk_f32 v2, v145, 0x3a800000, v191
	v_cmp_gt_f32_e32 vcc, s57, v2
	v_mul_f32_e32 v3, 0x4f800000, v2
	s_nop 0
	v_cndmask_b32_e32 v2, v2, v3, vcc
	v_sqrt_f32_e32 v3, v2
	s_nop 0
	v_add_u32_e32 v152, -1, v3
	v_fma_f32 v153, -v152, v3, v2
	v_cmp_ge_f32_e64 s[8:9], 0, v153
	v_add_u32_e32 v153, 1, v3
	s_nop 0
	v_cndmask_b32_e64 v152, v3, v152, s[8:9]
	v_fma_f32 v3, -v153, v3, v2
	v_cmp_lt_f32_e64 s[8:9], 0, v3
	s_nop 1
	v_cndmask_b32_e64 v3, v152, v153, s[8:9]
	v_mul_f32_e32 v152, 0x37800000, v3
	v_cndmask_b32_e32 v3, v3, v152, vcc
	v_cmp_class_f32_e32 vcc, v2, v192
	s_nop 1
	v_cndmask_b32_e32 v2, v3, v2, vcc
	v_mul_f32_e32 v2, v2, v1
	v_pk_mul_f32 v[34:35], v[34:35], v[2:3] op_sel_hi:[1,0]
	v_pk_mul_f32 v[32:33], v[32:33], v[2:3] op_sel_hi:[1,0]
	v_pk_mul_f32 v[30:31], v[30:31], v[2:3] op_sel_hi:[1,0]
	v_pk_mul_f32 v[28:29], v[28:29], v[2:3] op_sel_hi:[1,0]
	v_pk_mul_f32 v[26:27], v[26:27], v[2:3] op_sel_hi:[1,0]
	v_pk_mul_f32 v[24:25], v[24:25], v[2:3] op_sel_hi:[1,0]
	v_pk_mul_f32 v[22:23], v[22:23], v[2:3] op_sel_hi:[1,0]
	v_pk_mul_f32 v[20:21], v[20:21], v[2:3] op_sel_hi:[1,0]
	v_fmamk_f32 v1, v146, 0x3a800000, v191
	v_cmp_gt_f32_e32 vcc, s56, v1
	v_mul_f32_e32 v2, 0x4b800000, v1
	s_nop 0
	v_cndmask_b32_e32 v1, v1, v2, vcc
	v_rsq_f32_e32 v1, v1
	s_nop 0
	v_mul_f32_e32 v2, 0x45800000, v1
	v_cndmask_b32_e32 v1, v1, v2, vcc
	v_fmamk_f32 v2, v147, 0x3a800000, v191
	v_cmp_gt_f32_e32 vcc, s57, v2
	v_mul_f32_e32 v3, 0x4f800000, v2
	s_nop 0
	v_cndmask_b32_e32 v2, v2, v3, vcc
	v_sqrt_f32_e32 v3, v2
	s_nop 0
	v_add_u32_e32 v152, -1, v3
	v_fma_f32 v153, -v152, v3, v2
	v_cmp_ge_f32_e64 s[8:9], 0, v153
	v_add_u32_e32 v153, 1, v3
	s_nop 0
	v_cndmask_b32_e64 v152, v3, v152, s[8:9]
	v_fma_f32 v3, -v153, v3, v2
	v_cmp_lt_f32_e64 s[8:9], 0, v3
	s_nop 1
	v_cndmask_b32_e64 v3, v152, v153, s[8:9]
	v_mul_f32_e32 v152, 0x37800000, v3
	v_cndmask_b32_e32 v3, v3, v152, vcc
	v_cmp_class_f32_e32 vcc, v2, v192
	s_nop 1
	v_cndmask_b32_e32 v2, v3, v2, vcc
	v_mul_f32_e32 v2, v2, v1
	v_pk_mul_f32 v[18:19], v[18:19], v[2:3] op_sel_hi:[1,0]
	v_pk_mul_f32 v[16:17], v[16:17], v[2:3] op_sel_hi:[1,0]
	v_pk_mul_f32 v[14:15], v[14:15], v[2:3] op_sel_hi:[1,0]
	v_pk_mul_f32 v[12:13], v[12:13], v[2:3] op_sel_hi:[1,0]
	v_pk_mul_f32 v[10:11], v[10:11], v[2:3] op_sel_hi:[1,0]
	v_pk_mul_f32 v[8:9], v[8:9], v[2:3] op_sel_hi:[1,0]
	v_pk_mul_f32 v[6:7], v[6:7], v[2:3] op_sel_hi:[1,0]
	v_pk_mul_f32 v[4:5], v[4:5], v[2:3] op_sel_hi:[1,0]
	s_branch .LBB0_542

.LBB0_629:
	s_ashr_i32 s23, s22, 31
	s_lshl_b64 s[24:25], s[22:23], 19
	s_add_u32 s24, s14, s24
	s_addc_u32 s25, s15, s25
	s_and_b64 s[26:27], s[4:5], exec
	s_cselect_b32 s23, s25, s29
	s_cselect_b32 s33, s24, s28
	s_ashr_i32 s21, s20, 31
	s_lshl_b64 s[26:27], s[20:21], 19
	s_add_u32 s26, s74, s26
	s_addc_u32 s27, s75, s27
	s_and_b64 s[30:31], s[4:5], exec
	s_cselect_b32 s21, s27, s1
	s_cselect_b32 s42, s26, s0
	s_add_u32 s28, s28, 0x40080
	s_addc_u32 s29, s29, 0
	s_add_u32 s52, s0, 0x100
	v_mov_b32_e32 v36, 0
	s_addc_u32 s53, s1, 0
	s_mov_b32 s54, -2
	v_mov_b32_e32 v37, v36
	v_mov_b32_e32 v38, v36
	v_mov_b32_e32 v39, v36
	v_mov_b32_e32 v44, v36
	v_mov_b32_e32 v45, v36
	v_mov_b32_e32 v46, v36
	v_mov_b32_e32 v47, v36
	v_mov_b32_e32 v48, v36
	v_mov_b32_e32 v49, v36
	v_mov_b32_e32 v50, v36
	v_mov_b32_e32 v51, v36
	v_mov_b32_e32 v60, v36
	v_mov_b32_e32 v61, v36
	v_mov_b32_e32 v62, v36
	v_mov_b32_e32 v63, v36
	v_mov_b32_e32 v64, v36
	v_mov_b32_e32 v65, v36
	v_mov_b32_e32 v66, v36
	v_mov_b32_e32 v67, v36
	v_mov_b32_e32 v76, v36
	v_mov_b32_e32 v77, v36
	v_mov_b32_e32 v78, v36
	v_mov_b32_e32 v79, v36
	s_waitcnt vmcnt(0)
	v_mov_b32_e32 v80, v36
	v_mov_b32_e32 v81, v36
	v_mov_b32_e32 v82, v36
	v_mov_b32_e32 v83, v36
	v_mov_b32_e32 v92, v36
	v_mov_b32_e32 v93, v36
	v_mov_b32_e32 v94, v36
	v_mov_b32_e32 v95, v36
	v_mov_b32_e32 v32, v36
	v_mov_b32_e32 v33, v36
	v_mov_b32_e32 v34, v36
	v_mov_b32_e32 v35, v36
	v_mov_b32_e32 v40, v36
	v_mov_b32_e32 v41, v36
	v_mov_b32_e32 v42, v36
	v_mov_b32_e32 v43, v36
	v_mov_b32_e32 v52, v36
	v_mov_b32_e32 v53, v36
	v_mov_b32_e32 v54, v36
	v_mov_b32_e32 v55, v36
	v_mov_b32_e32 v56, v36
	v_mov_b32_e32 v57, v36
	v_mov_b32_e32 v58, v36
	v_mov_b32_e32 v59, v36
	v_mov_b32_e32 v68, v36
	v_mov_b32_e32 v69, v36
	v_mov_b32_e32 v70, v36
	v_mov_b32_e32 v71, v36
	v_mov_b32_e32 v72, v36
	v_mov_b32_e32 v73, v36
	v_mov_b32_e32 v74, v36
	v_mov_b32_e32 v75, v36
	v_mov_b32_e32 v84, v36
	v_mov_b32_e32 v85, v36
	v_mov_b32_e32 v86, v36
	v_mov_b32_e32 v87, v36
	v_mov_b32_e32 v88, v36
	v_mov_b32_e32 v89, v36
	v_mov_b32_e32 v90, v36
	v_mov_b32_e32 v91, v36
	v_mov_b32_e32 v96, v36
	v_mov_b32_e32 v97, v36
	v_mov_b32_e32 v98, v36
	v_mov_b32_e32 v99, v36
	v_mov_b32_e32 v108, v36
	v_mov_b32_e32 v109, v36
	v_mov_b32_e32 v110, v36
	v_mov_b32_e32 v111, v36
	v_mov_b32_e32 v112, v36
	v_mov_b32_e32 v113, v36
	v_mov_b32_e32 v114, v36
	v_mov_b32_e32 v115, v36
	v_mov_b32_e32 v124, v36
	v_mov_b32_e32 v125, v36
	v_mov_b32_e32 v126, v36
	v_mov_b32_e32 v127, v36
	v_mov_b32_e32 v128, v36
	v_mov_b32_e32 v129, v36
	v_mov_b32_e32 v130, v36
	v_mov_b32_e32 v131, v36
	v_mov_b32_e32 v140, v36
	v_mov_b32_e32 v141, v36
	v_mov_b32_e32 v142, v36
	v_mov_b32_e32 v143, v36
	v_mov_b32_e32 v144, v36
	v_mov_b32_e32 v145, v36
	v_mov_b32_e32 v146, v36
	v_mov_b32_e32 v147, v36
	v_mov_b32_e32 v156, v36
	v_mov_b32_e32 v157, v36
	v_mov_b32_e32 v158, v36
	v_mov_b32_e32 v159, v36
	v_mov_b32_e32 v100, v36
	v_mov_b32_e32 v101, v36
	v_mov_b32_e32 v102, v36
	v_mov_b32_e32 v103, v36
	v_mov_b32_e32 v104, v36
	v_mov_b32_e32 v105, v36
	v_mov_b32_e32 v106, v36
	v_mov_b32_e32 v107, v36
	v_mov_b32_e32 v116, v36
	v_mov_b32_e32 v117, v36
	v_mov_b32_e32 v118, v36
	v_mov_b32_e32 v119, v36
	v_mov_b32_e32 v120, v36
	v_mov_b32_e32 v121, v36
	v_mov_b32_e32 v122, v36
	v_mov_b32_e32 v123, v36
	v_mov_b32_e32 v132, v36
	v_mov_b32_e32 v133, v36
	v_mov_b32_e32 v134, v36
	v_mov_b32_e32 v135, v36
	v_mov_b32_e32 v136, v36
	v_mov_b32_e32 v137, v36
	v_mov_b32_e32 v138, v36
	v_mov_b32_e32 v139, v36
	v_mov_b32_e32 v148, v36
	v_mov_b32_e32 v149, v36
	v_mov_b32_e32 v150, v36
	v_mov_b32_e32 v151, v36
	v_mov_b32_e32 v152, v36
	v_mov_b32_e32 v153, v36
	v_mov_b32_e32 v154, v36
	v_mov_b32_e32 v155, v36
	v_lshl_add_u32 v246, s6, 8, v194
	v_ashrrev_i32_e32 v247, 31, v246
	v_lshl_add_u64 v[246:247], v[246:247], 2, s[12:13]
	global_load_dword v238, v[246:247], off
	global_load_dword v239, v[246:247], off offset:64
	global_load_dword v240, v[246:247], off offset:128
	global_load_dword v241, v[246:247], off offset:192
	global_load_dword v242, v[246:247], off offset:512
	global_load_dword v243, v[246:247], off offset:576
	global_load_dword v244, v[246:247], off offset:640
	global_load_dword v245, v[246:247], off offset:704

.LBB0_633:
	v_lshl_add_u32 v0, s6, 8, v194
	v_ashrrev_i32_e32 v1, 31, v0
	v_lshl_add_u64 v[0:1], v[0:1], 2, s[12:13]
	s_nop 0
	s_lshl_b32 s0, s7, 7
	s_or_b32 s0, s0, s83
	s_ashr_i32 s0, s0, 6
	s_mul_hi_i32 s1, s6, 0x56
	s_mulk_i32 s6, 0x56
	s_ashr_i32 s7, s0, 31
	s_add_u32 s0, s6, s0
	s_addc_u32 s1, s1, s7
	v_pk_mul_f32 v[4:5], v[152:153], v[156:157]
	s_lshl_b64 s[0:1], s[0:1], 15
	v_pk_mul_f32 v[2:3], v[154:155], v[158:159]
	v_pk_mul_f32 v[6:7], v[150:151], v[146:147]
	v_pk_mul_f32 v[8:9], v[148:149], v[144:145]
	v_fmamk_f32 v10, v238, 0x3a000000, v200
	v_mul_f32_e32 v11, 0x4b800000, v10
	v_cmp_gt_f32_e32 vcc, s51, v10
	s_nop 1
	v_cndmask_b32_e32 v10, v10, v11, vcc
	v_rsq_f32_e32 v12, v10
	v_lshl_add_u64 v[10:11], v[170:171], 0, s[0:1]
	v_mul_f32_e32 v13, 0x45800000, v12
	v_cndmask_b32_e32 v12, v12, v13, vcc
	v_mul_f32_e32 v13, 0x3b800000, v12
	v_mul_f32_e32 v12, 0xbfb8aa3b, v13
	v_pk_mul_f32 v[16:17], v[152:153], v[12:13] op_sel_hi:[1,0]
	v_mul_f32_e32 v14, v13, v13
	v_pk_mul_f32 v[18:19], v[154:155], v[12:13] op_sel_hi:[1,0]
	v_pk_mul_f32 v[20:21], v[148:149], v[12:13] op_sel_hi:[1,0]
	v_pk_mul_f32 v[12:13], v[150:151], v[12:13] op_sel_hi:[1,0]
	v_exp_f32_e32 v16, v16
	v_exp_f32_e32 v17, v17
	v_exp_f32_e32 v18, v18
	v_exp_f32_e32 v19, v19
	v_exp_f32_e32 v20, v20
	v_exp_f32_e32 v21, v21
	v_exp_f32_e32 v12, v12
	v_exp_f32_e32 v13, v13
	v_pk_add_f32 v[16:17], v[16:17], 1.0 op_sel_hi:[1,0]
	v_pk_add_f32 v[18:19], v[18:19], 1.0 op_sel_hi:[1,0]
	v_pk_add_f32 v[20:21], v[20:21], 1.0 op_sel_hi:[1,0]
	v_pk_add_f32 v[12:13], v[12:13], 1.0 op_sel_hi:[1,0]
	v_rcp_f32_e32 v16, v16
	v_rcp_f32_e32 v17, v17
	v_rcp_f32_e32 v18, v18
	v_rcp_f32_e32 v19, v19
	v_rcp_f32_e32 v20, v20
	v_rcp_f32_e32 v21, v21
	v_rcp_f32_e32 v12, v12
	v_rcp_f32_e32 v13, v13
	v_pk_mul_f32 v[16:17], v[14:15], v[16:17] op_sel_hi:[0,1]
	v_pk_mul_f32 v[18:19], v[14:15], v[18:19] op_sel_hi:[0,1]
	v_pk_mul_f32 v[20:21], v[14:15], v[20:21] op_sel_hi:[0,1]
	v_pk_mul_f32 v[12:13], v[14:15], v[12:13] op_sel_hi:[0,1]
	v_pk_mul_f32 v[4:5], v[4:5], v[16:17]
	v_pk_mul_f32 v[14:15], v[2:3], v[18:19]
	v_pk_mul_f32 v[8:9], v[8:9], v[20:21]
	v_pk_mul_f32 v[6:7], v[6:7], v[12:13]
	v_cvt_pk_bf16_f32 v2, v4, v5
	v_cvt_pk_bf16_f32 v3, v14, v15
	v_cvt_pk_bf16_f32 v4, v8, v9
	v_pk_mul_f32 v[8:9], v[132:133], v[128:129]
	v_cvt_pk_bf16_f32 v5, v6, v7
	global_store_dwordx4 v[10:11], v[2:5], off nt
	s_nop 0
	v_lshl_add_u64 v[10:11], v[172:173], 0, s[0:1]
	v_pk_mul_f32 v[4:5], v[136:137], v[140:141]
	v_pk_mul_f32 v[2:3], v[138:139], v[142:143]
	v_fmamk_f32 v6, v239, 0x3a000000, v200
	v_mul_f32_e32 v7, 0x4b800000, v6
	v_cmp_gt_f32_e32 vcc, s51, v6
	s_nop 1
	v_cndmask_b32_e32 v6, v6, v7, vcc
	v_rsq_f32_e32 v12, v6
	v_pk_mul_f32 v[6:7], v[134:135], v[130:131]
	v_mul_f32_e32 v13, 0x45800000, v12
	v_cndmask_b32_e32 v12, v12, v13, vcc
	v_mul_f32_e32 v13, 0x3b800000, v12
	v_mul_f32_e32 v12, 0xbfb8aa3b, v13
	v_pk_mul_f32 v[16:17], v[136:137], v[12:13] op_sel_hi:[1,0]
	v_mul_f32_e32 v14, v13, v13
	v_pk_mul_f32 v[18:19], v[138:139], v[12:13] op_sel_hi:[1,0]
	v_pk_mul_f32 v[20:21], v[132:133], v[12:13] op_sel_hi:[1,0]
	v_pk_mul_f32 v[12:13], v[134:135], v[12:13] op_sel_hi:[1,0]
	v_exp_f32_e32 v16, v16
	v_exp_f32_e32 v17, v17
	v_exp_f32_e32 v18, v18
	v_exp_f32_e32 v19, v19
	v_exp_f32_e32 v20, v20
	v_exp_f32_e32 v21, v21
	v_exp_f32_e32 v12, v12
	v_exp_f32_e32 v13, v13
	v_pk_add_f32 v[16:17], v[16:17], 1.0 op_sel_hi:[1,0]
	v_pk_add_f32 v[18:19], v[18:19], 1.0 op_sel_hi:[1,0]
	v_pk_add_f32 v[20:21], v[20:21], 1.0 op_sel_hi:[1,0]
	v_pk_add_f32 v[12:13], v[12:13], 1.0 op_sel_hi:[1,0]
	v_rcp_f32_e32 v16, v16
	v_rcp_f32_e32 v17, v17
	v_rcp_f32_e32 v18, v18
	v_rcp_f32_e32 v19, v19
	v_rcp_f32_e32 v20, v20
	v_rcp_f32_e32 v21, v21
	v_rcp_f32_e32 v12, v12
	v_rcp_f32_e32 v13, v13
	v_pk_mul_f32 v[16:17], v[14:15], v[16:17] op_sel_hi:[0,1]
	v_pk_mul_f32 v[18:19], v[14:15], v[18:19] op_sel_hi:[0,1]
	v_pk_mul_f32 v[20:21], v[14:15], v[20:21] op_sel_hi:[0,1]
	v_pk_mul_f32 v[12:13], v[14:15], v[12:13] op_sel_hi:[0,1]
	v_pk_mul_f32 v[4:5], v[4:5], v[16:17]
	v_pk_mul_f32 v[14:15], v[2:3], v[18:19]
	v_pk_mul_f32 v[8:9], v[8:9], v[20:21]
	v_pk_mul_f32 v[6:7], v[6:7], v[12:13]
	v_cvt_pk_bf16_f32 v2, v4, v5
	v_cvt_pk_bf16_f32 v3, v14, v15
	v_cvt_pk_bf16_f32 v4, v8, v9
	v_pk_mul_f32 v[8:9], v[116:117], v[112:113]
	v_cvt_pk_bf16_f32 v5, v6, v7
	global_store_dwordx4 v[10:11], v[2:5], off nt
	s_nop 0
	v_lshl_add_u64 v[10:11], v[174:175], 0, s[0:1]
	v_pk_mul_f32 v[4:5], v[120:121], v[124:125]
	v_pk_mul_f32 v[2:3], v[122:123], v[126:127]
	v_fmamk_f32 v6, v240, 0x3a000000, v200
	v_mul_f32_e32 v7, 0x4b800000, v6
	v_cmp_gt_f32_e32 vcc, s51, v6
	s_nop 1
	v_cndmask_b32_e32 v6, v6, v7, vcc
	v_rsq_f32_e32 v12, v6
	v_pk_mul_f32 v[6:7], v[118:119], v[114:115]
	v_mul_f32_e32 v13, 0x45800000, v12
	v_cndmask_b32_e32 v12, v12, v13, vcc
	v_mul_f32_e32 v13, 0x3b800000, v12
	v_mul_f32_e32 v12, 0xbfb8aa3b, v13
	v_pk_mul_f32 v[16:17], v[120:121], v[12:13] op_sel_hi:[1,0]
	v_mul_f32_e32 v14, v13, v13
	v_pk_mul_f32 v[18:19], v[122:123], v[12:13] op_sel_hi:[1,0]
	v_pk_mul_f32 v[20:21], v[116:117], v[12:13] op_sel_hi:[1,0]
	v_pk_mul_f32 v[12:13], v[118:119], v[12:13] op_sel_hi:[1,0]
	v_exp_f32_e32 v16, v16
	v_exp_f32_e32 v17, v17
	v_exp_f32_e32 v18, v18
	v_exp_f32_e32 v19, v19
	v_exp_f32_e32 v20, v20
	v_exp_f32_e32 v21, v21
	v_exp_f32_e32 v12, v12
	v_exp_f32_e32 v13, v13
	v_pk_add_f32 v[16:17], v[16:17], 1.0 op_sel_hi:[1,0]
	v_pk_add_f32 v[18:19], v[18:19], 1.0 op_sel_hi:[1,0]
	v_pk_add_f32 v[20:21], v[20:21], 1.0 op_sel_hi:[1,0]
	v_pk_add_f32 v[12:13], v[12:13], 1.0 op_sel_hi:[1,0]
	v_rcp_f32_e32 v16, v16
	v_rcp_f32_e32 v17, v17
	v_rcp_f32_e32 v18, v18
	v_rcp_f32_e32 v19, v19
	v_rcp_f32_e32 v20, v20
	v_rcp_f32_e32 v21, v21
	v_rcp_f32_e32 v12, v12
	v_rcp_f32_e32 v13, v13
	v_pk_mul_f32 v[16:17], v[14:15], v[16:17] op_sel_hi:[0,1]
	v_pk_mul_f32 v[18:19], v[14:15], v[18:19] op_sel_hi:[0,1]
	v_pk_mul_f32 v[20:21], v[14:15], v[20:21] op_sel_hi:[0,1]
	v_pk_mul_f32 v[12:13], v[14:15], v[12:13] op_sel_hi:[0,1]
	v_pk_mul_f32 v[4:5], v[4:5], v[16:17]
	v_pk_mul_f32 v[14:15], v[2:3], v[18:19]
	v_pk_mul_f32 v[8:9], v[8:9], v[20:21]
	v_pk_mul_f32 v[6:7], v[6:7], v[12:13]
	v_cvt_pk_bf16_f32 v2, v4, v5
	v_cvt_pk_bf16_f32 v3, v14, v15
	v_cvt_pk_bf16_f32 v4, v8, v9
	v_pk_mul_f32 v[8:9], v[100:101], v[96:97]
	v_cvt_pk_bf16_f32 v5, v6, v7
	global_store_dwordx4 v[10:11], v[2:5], off nt
	s_nop 0
	v_lshl_add_u64 v[10:11], v[176:177], 0, s[0:1]
	v_pk_mul_f32 v[4:5], v[104:105], v[108:109]
	v_pk_mul_f32 v[2:3], v[106:107], v[110:111]
	s_add_u32 s0, s48, s0
	s_addc_u32 s1, s49, s1
	s_add_u32 s0, s0, 0x4000
	s_addc_u32 s1, s1, 0
	v_fmamk_f32 v6, v241, 0x3a000000, v200
	v_mul_f32_e32 v7, 0x4b800000, v6
	v_cmp_gt_f32_e32 vcc, s51, v6
	s_nop 1
	v_cndmask_b32_e32 v6, v6, v7, vcc
	v_rsq_f32_e32 v12, v6
	v_pk_mul_f32 v[6:7], v[102:103], v[98:99]
	v_mul_f32_e32 v13, 0x45800000, v12
	v_cndmask_b32_e32 v12, v12, v13, vcc
	v_mul_f32_e32 v13, 0x3b800000, v12
	v_mul_f32_e32 v12, 0xbfb8aa3b, v13
	v_pk_mul_f32 v[16:17], v[104:105], v[12:13] op_sel_hi:[1,0]
	v_mul_f32_e32 v14, v13, v13
	v_pk_mul_f32 v[18:19], v[106:107], v[12:13] op_sel_hi:[1,0]
	v_pk_mul_f32 v[20:21], v[100:101], v[12:13] op_sel_hi:[1,0]
	v_pk_mul_f32 v[12:13], v[102:103], v[12:13] op_sel_hi:[1,0]
	v_exp_f32_e32 v16, v16
	v_exp_f32_e32 v17, v17
	v_exp_f32_e32 v18, v18
	v_exp_f32_e32 v19, v19
	v_exp_f32_e32 v20, v20
	v_exp_f32_e32 v21, v21
	v_exp_f32_e32 v12, v12
	v_exp_f32_e32 v13, v13
	v_pk_add_f32 v[16:17], v[16:17], 1.0 op_sel_hi:[1,0]
	v_pk_add_f32 v[18:19], v[18:19], 1.0 op_sel_hi:[1,0]
	v_pk_add_f32 v[20:21], v[20:21], 1.0 op_sel_hi:[1,0]
	v_pk_add_f32 v[12:13], v[12:13], 1.0 op_sel_hi:[1,0]
	v_rcp_f32_e32 v16, v16
	v_rcp_f32_e32 v17, v17
	v_rcp_f32_e32 v18, v18
	v_rcp_f32_e32 v19, v19
	v_rcp_f32_e32 v20, v20
	v_rcp_f32_e32 v21, v21
	v_rcp_f32_e32 v12, v12
	v_rcp_f32_e32 v13, v13
	v_pk_mul_f32 v[16:17], v[14:15], v[16:17] op_sel_hi:[0,1]
	v_pk_mul_f32 v[18:19], v[14:15], v[18:19] op_sel_hi:[0,1]
	v_pk_mul_f32 v[20:21], v[14:15], v[20:21] op_sel_hi:[0,1]
	v_pk_mul_f32 v[12:13], v[14:15], v[12:13] op_sel_hi:[0,1]
	v_pk_mul_f32 v[4:5], v[4:5], v[16:17]
	v_pk_mul_f32 v[14:15], v[2:3], v[18:19]
	v_pk_mul_f32 v[8:9], v[8:9], v[20:21]
	v_pk_mul_f32 v[6:7], v[6:7], v[12:13]
	v_cvt_pk_bf16_f32 v2, v4, v5
	v_cvt_pk_bf16_f32 v3, v14, v15
	v_cvt_pk_bf16_f32 v4, v8, v9
	v_pk_mul_f32 v[8:9], v[84:85], v[80:81]
	v_cvt_pk_bf16_f32 v5, v6, v7
	global_store_dwordx4 v[10:11], v[2:5], off nt
	s_nop 0
	v_pk_mul_f32 v[6:7], v[86:87], v[82:83]
	v_pk_mul_f32 v[4:5], v[88:89], v[92:93]
	v_pk_mul_f32 v[2:3], v[90:91], v[94:95]
	v_fmamk_f32 v10, v242, 0x3a000000, v200
	v_mul_f32_e32 v11, 0x4b800000, v10
	v_cmp_gt_f32_e32 vcc, s51, v10
	s_nop 1
	v_cndmask_b32_e32 v10, v10, v11, vcc
	v_rsq_f32_e32 v12, v10
	v_lshl_add_u64 v[10:11], v[168:169], 1, s[0:1]
	v_mul_f32_e32 v13, 0x45800000, v12
	v_cndmask_b32_e32 v12, v12, v13, vcc
	v_mul_f32_e32 v13, 0x3b800000, v12
	v_mul_f32_e32 v12, 0xbfb8aa3b, v13
	v_pk_mul_f32 v[16:17], v[88:89], v[12:13] op_sel_hi:[1,0]
	v_mul_f32_e32 v14, v13, v13
	v_pk_mul_f32 v[18:19], v[90:91], v[12:13] op_sel_hi:[1,0]
	v_pk_mul_f32 v[20:21], v[84:85], v[12:13] op_sel_hi:[1,0]
	v_pk_mul_f32 v[12:13], v[86:87], v[12:13] op_sel_hi:[1,0]
	v_exp_f32_e32 v16, v16
	v_exp_f32_e32 v17, v17
	v_exp_f32_e32 v18, v18
	v_exp_f32_e32 v19, v19
	v_exp_f32_e32 v20, v20
	v_exp_f32_e32 v21, v21
	v_exp_f32_e32 v12, v12
	v_exp_f32_e32 v13, v13
	v_pk_add_f32 v[16:17], v[16:17], 1.0 op_sel_hi:[1,0]
	v_pk_add_f32 v[18:19], v[18:19], 1.0 op_sel_hi:[1,0]
	v_pk_add_f32 v[20:21], v[20:21], 1.0 op_sel_hi:[1,0]
	v_pk_add_f32 v[12:13], v[12:13], 1.0 op_sel_hi:[1,0]
	v_rcp_f32_e32 v16, v16
	v_rcp_f32_e32 v17, v17
	v_rcp_f32_e32 v18, v18
	v_rcp_f32_e32 v19, v19
	v_rcp_f32_e32 v20, v20
	v_rcp_f32_e32 v21, v21
	v_rcp_f32_e32 v12, v12
	v_rcp_f32_e32 v13, v13
	v_pk_mul_f32 v[16:17], v[14:15], v[16:17] op_sel_hi:[0,1]
	v_pk_mul_f32 v[18:19], v[14:15], v[18:19] op_sel_hi:[0,1]
	v_pk_mul_f32 v[20:21], v[14:15], v[20:21] op_sel_hi:[0,1]
	v_pk_mul_f32 v[12:13], v[14:15], v[12:13] op_sel_hi:[0,1]
	v_pk_mul_f32 v[4:5], v[4:5], v[16:17]
	v_pk_mul_f32 v[14:15], v[2:3], v[18:19]
	v_pk_mul_f32 v[8:9], v[8:9], v[20:21]
	v_pk_mul_f32 v[6:7], v[6:7], v[12:13]
	v_cvt_pk_bf16_f32 v2, v4, v5
	v_cvt_pk_bf16_f32 v3, v14, v15
	v_cvt_pk_bf16_f32 v4, v8, v9
	v_pk_mul_f32 v[8:9], v[68:69], v[64:65]
	v_cvt_pk_bf16_f32 v5, v6, v7
	global_store_dwordx4 v[10:11], v[2:5], off nt
	s_nop 0
	v_pk_mul_f32 v[6:7], v[70:71], v[66:67]
	v_pk_mul_f32 v[2:3], v[74:75], v[78:79]
	v_fmamk_f32 v4, v243, 0x3a000000, v200
	v_mul_f32_e32 v5, 0x4b800000, v4
	v_cmp_gt_f32_e32 vcc, s51, v4
	s_nop 1
	v_cndmask_b32_e32 v4, v4, v5, vcc
	v_rsq_f32_e32 v10, v4
	v_pk_mul_f32 v[4:5], v[72:73], v[76:77]
	v_mul_f32_e32 v11, 0x45800000, v10
	v_cndmask_b32_e32 v10, v10, v11, vcc
	v_mul_f32_e32 v11, 0x3b800000, v10
	v_mul_f32_e32 v10, 0xbfb8aa3b, v11
	v_pk_mul_f32 v[14:15], v[72:73], v[10:11] op_sel_hi:[1,0]
	v_mul_f32_e32 v12, v11, v11
	v_pk_mul_f32 v[16:17], v[74:75], v[10:11] op_sel_hi:[1,0]
	v_pk_mul_f32 v[18:19], v[68:69], v[10:11] op_sel_hi:[1,0]
	v_pk_mul_f32 v[10:11], v[70:71], v[10:11] op_sel_hi:[1,0]
	v_exp_f32_e32 v14, v14
	v_exp_f32_e32 v15, v15
	v_exp_f32_e32 v16, v16
	v_exp_f32_e32 v17, v17
	v_exp_f32_e32 v18, v18
	v_exp_f32_e32 v19, v19
	v_exp_f32_e32 v10, v10
	v_exp_f32_e32 v11, v11
	v_pk_add_f32 v[14:15], v[14:15], 1.0 op_sel_hi:[1,0]
	v_pk_add_f32 v[16:17], v[16:17], 1.0 op_sel_hi:[1,0]
	v_pk_add_f32 v[18:19], v[18:19], 1.0 op_sel_hi:[1,0]
	v_pk_add_f32 v[10:11], v[10:11], 1.0 op_sel_hi:[1,0]
	v_rcp_f32_e32 v14, v14
	v_rcp_f32_e32 v15, v15
	v_rcp_f32_e32 v16, v16
	v_rcp_f32_e32 v17, v17
	v_rcp_f32_e32 v18, v18
	v_rcp_f32_e32 v19, v19
	v_rcp_f32_e32 v10, v10
	v_rcp_f32_e32 v11, v11
	v_pk_mul_f32 v[14:15], v[12:13], v[14:15] op_sel_hi:[0,1]
	v_pk_mul_f32 v[16:17], v[12:13], v[16:17] op_sel_hi:[0,1]
	v_pk_mul_f32 v[18:19], v[12:13], v[18:19] op_sel_hi:[0,1]
	v_pk_mul_f32 v[10:11], v[12:13], v[10:11] op_sel_hi:[0,1]
	v_pk_mul_f32 v[4:5], v[4:5], v[14:15]
	v_pk_mul_f32 v[12:13], v[2:3], v[16:17]
	v_pk_mul_f32 v[8:9], v[8:9], v[18:19]
	v_pk_mul_f32 v[6:7], v[6:7], v[10:11]
	v_cvt_pk_bf16_f32 v2, v4, v5
	v_cvt_pk_bf16_f32 v3, v12, v13
	v_cvt_pk_bf16_f32 v4, v8, v9
	v_pk_mul_f32 v[8:9], v[52:53], v[48:49]
	v_cvt_pk_bf16_f32 v5, v6, v7
	global_store_dwordx4 v201, v[2:5], s[0:1] nt
	s_nop 0
	v_pk_mul_f32 v[6:7], v[54:55], v[50:51]
	v_pk_mul_f32 v[2:3], v[58:59], v[62:63]
	v_fmamk_f32 v4, v244, 0x3a000000, v200
	v_mul_f32_e32 v5, 0x4b800000, v4
	v_cmp_gt_f32_e32 vcc, s51, v4
	s_nop 1
	v_cndmask_b32_e32 v4, v4, v5, vcc
	v_rsq_f32_e32 v10, v4
	v_pk_mul_f32 v[4:5], v[56:57], v[60:61]
	v_mul_f32_e32 v11, 0x45800000, v10
	v_cndmask_b32_e32 v10, v10, v11, vcc
	v_mul_f32_e32 v11, 0x3b800000, v10
	v_mul_f32_e32 v10, 0xbfb8aa3b, v11
	v_pk_mul_f32 v[14:15], v[56:57], v[10:11] op_sel_hi:[1,0]
	v_mul_f32_e32 v12, v11, v11
	v_pk_mul_f32 v[16:17], v[58:59], v[10:11] op_sel_hi:[1,0]
	v_pk_mul_f32 v[18:19], v[52:53], v[10:11] op_sel_hi:[1,0]
	v_pk_mul_f32 v[10:11], v[54:55], v[10:11] op_sel_hi:[1,0]
	v_exp_f32_e32 v14, v14
	v_exp_f32_e32 v15, v15
	v_exp_f32_e32 v16, v16
	v_exp_f32_e32 v17, v17
	v_exp_f32_e32 v18, v18
	v_exp_f32_e32 v19, v19
	v_exp_f32_e32 v10, v10
	v_exp_f32_e32 v11, v11
	v_pk_add_f32 v[14:15], v[14:15], 1.0 op_sel_hi:[1,0]
	v_pk_add_f32 v[16:17], v[16:17], 1.0 op_sel_hi:[1,0]
	v_pk_add_f32 v[18:19], v[18:19], 1.0 op_sel_hi:[1,0]
	v_pk_add_f32 v[10:11], v[10:11], 1.0 op_sel_hi:[1,0]
	v_rcp_f32_e32 v14, v14
	v_rcp_f32_e32 v15, v15
	v_rcp_f32_e32 v16, v16
	v_rcp_f32_e32 v17, v17
	v_rcp_f32_e32 v18, v18
	v_rcp_f32_e32 v19, v19
	v_rcp_f32_e32 v10, v10
	v_rcp_f32_e32 v11, v11
	v_pk_mul_f32 v[14:15], v[12:13], v[14:15] op_sel_hi:[0,1]
	v_pk_mul_f32 v[16:17], v[12:13], v[16:17] op_sel_hi:[0,1]
	v_pk_mul_f32 v[18:19], v[12:13], v[18:19] op_sel_hi:[0,1]
	v_pk_mul_f32 v[10:11], v[12:13], v[10:11] op_sel_hi:[0,1]
	v_pk_mul_f32 v[4:5], v[4:5], v[14:15]
	v_pk_mul_f32 v[12:13], v[2:3], v[16:17]
	v_pk_mul_f32 v[8:9], v[8:9], v[18:19]
	v_pk_mul_f32 v[6:7], v[6:7], v[10:11]
	v_cvt_pk_bf16_f32 v2, v4, v5
	v_cvt_pk_bf16_f32 v3, v12, v13
	v_cvt_pk_bf16_f32 v4, v8, v9
	s_andn2_b64 vcc, exec, s[4:5]
	v_cvt_pk_bf16_f32 v5, v6, v7
	global_store_dwordx4 v202, v[2:5], s[0:1] nt
	s_nop 0
	v_pk_mul_f32 v[0:1], v[42:43], v[46:47]
	v_pk_mul_f32 v[2:3], v[40:41], v[44:45]
	v_pk_mul_f32 v[4:5], v[34:35], v[38:39]
	v_pk_mul_f32 v[6:7], v[32:33], v[36:37]
	v_fmamk_f32 v8, v245, 0x3a000000, v200
	v_mul_f32_e32 v9, 0x4b800000, v8
	v_cmp_gt_f32_e64 s[6:7], s51, v8
	s_nop 1
	v_cndmask_b32_e64 v8, v8, v9, s[6:7]
	v_rsq_f32_e32 v8, v8
	s_nop 0
	v_mul_f32_e32 v9, 0x45800000, v8
	v_cndmask_b32_e64 v8, v8, v9, s[6:7]
	v_mul_f32_e32 v9, 0x3b800000, v8
	v_mul_f32_e32 v8, 0xbfb8aa3b, v9
	v_pk_mul_f32 v[12:13], v[40:41], v[8:9] op_sel_hi:[1,0]
	v_mul_f32_e32 v10, v9, v9
	v_pk_mul_f32 v[14:15], v[42:43], v[8:9] op_sel_hi:[1,0]
	v_pk_mul_f32 v[16:17], v[32:33], v[8:9] op_sel_hi:[1,0]
	v_pk_mul_f32 v[8:9], v[34:35], v[8:9] op_sel_hi:[1,0]
	v_exp_f32_e32 v12, v12
	v_exp_f32_e32 v13, v13
	v_exp_f32_e32 v14, v14
	v_exp_f32_e32 v15, v15
	v_exp_f32_e32 v16, v16
	v_exp_f32_e32 v17, v17
	v_exp_f32_e32 v8, v8
	v_exp_f32_e32 v9, v9
	v_pk_add_f32 v[12:13], v[12:13], 1.0 op_sel_hi:[1,0]
	v_pk_add_f32 v[14:15], v[14:15], 1.0 op_sel_hi:[1,0]
	v_pk_add_f32 v[16:17], v[16:17], 1.0 op_sel_hi:[1,0]
	v_pk_add_f32 v[8:9], v[8:9], 1.0 op_sel_hi:[1,0]
	v_rcp_f32_e32 v12, v12
	v_rcp_f32_e32 v13, v13
	v_rcp_f32_e32 v14, v14
	v_rcp_f32_e32 v15, v15
	v_rcp_f32_e32 v16, v16
	v_rcp_f32_e32 v17, v17
	v_rcp_f32_e32 v8, v8
	v_rcp_f32_e32 v9, v9
	v_pk_mul_f32 v[12:13], v[10:11], v[12:13] op_sel_hi:[0,1]
	v_pk_mul_f32 v[14:15], v[10:11], v[14:15] op_sel_hi:[0,1]
	v_pk_mul_f32 v[16:17], v[10:11], v[16:17] op_sel_hi:[0,1]
	v_pk_mul_f32 v[8:9], v[10:11], v[8:9] op_sel_hi:[0,1]
	v_pk_mul_f32 v[2:3], v[2:3], v[12:13]
	v_pk_mul_f32 v[10:11], v[0:1], v[14:15]
	v_pk_mul_f32 v[6:7], v[6:7], v[16:17]
	v_pk_mul_f32 v[4:5], v[4:5], v[8:9]
	v_cvt_pk_bf16_f32 v0, v2, v3
	v_cvt_pk_bf16_f32 v1, v10, v11
	v_cvt_pk_bf16_f32 v2, v6, v7
	s_nop 0
	v_cvt_pk_bf16_f32 v3, v4, v5
	global_store_dwordx4 v203, v[0:3], s[0:1] nt
	s_mov_b64 s[0:1], -1
	s_cbranch_vccnz .LBB0_626
	s_andn2_b64 vcc, exec, s[8:9]
	s_cbranch_vccnz .LBB0_625
	s_barrier
	s_branch .LBB0_625
